# attention: first-tile-of-pair K fragment LDS reads issued right after the pair barrier, ahead of the next pair DMA issue block
# baseline (speedup 1.0000x reference)
.Latt_q_resident:
	s_cmp_gt_i32 s23, s86
	s_cbranch_scc1 .Latt_k_skip
	s_mul_i32 s13, s27, 0x6000
	v_add_u32_e32 v0, s13, v205
	v_add_u32_e32 v82, s13, v206
	v_add_u32_e32 v83, s13, v207
	v_add_u32_e32 v84, s13, v208
	ds_read_b128 v[174:177], v0
	ds_read_b128 v[190:193], v0 offset:4096
	ds_read_b128 v[178:181], v82
	ds_read_b128 v[194:197], v82 offset:4096
	ds_read_b128 v[182:185], v83
	ds_read_b128 v[198:201], v83 offset:4096
	ds_read_b128 v[186:189], v84
	ds_read_b128 v[220:223], v84 offset:4096

.LBB0_514:
	s_cmp_gt_i32 s23, s86
	s_cbranch_scc1 .LBB0_510
	s_mul_i32 s13, s27, 0x6000
	s_add_i32 s13, s13, 0
	s_cmpk_gt_i32 s25, 0x70
	s_cselect_b64 vcc, -1, 0
	s_add_i32 s28, s13, 0x2000
	v_add_u32_e32 v156, s28, v205
.Latt_k_prefetched:
	s_waitcnt lgkmcnt(8)
	v_cndmask_b32_e32 v157, 0, v238, vcc
	v_xor_b32_e32 v0, 32, v156
	v_sub_f32_e32 v66, v157, v154
	v_mov_b32_e32 v67, v66
	v_mov_b32_e32 v68, v66
	v_mov_b32_e32 v69, v66
	v_mov_b32_e32 v70, v66
	v_mov_b32_e32 v71, v66
	v_mov_b32_e32 v72, v66
	v_mov_b32_e32 v73, v66
	v_mov_b32_e32 v74, v66
	v_mov_b32_e32 v75, v66
	v_mov_b32_e32 v76, v66
	v_mov_b32_e32 v77, v66
	v_mov_b32_e32 v78, v66
	v_mov_b32_e32 v79, v66
	v_mov_b32_e32 v80, v66
	v_mov_b32_e32 v81, v66
	s_and_b64 vcc, exec, vcc
	s_nop 0
	s_waitcnt lgkmcnt(7)
	v_mfma_f32_32x32x16_bf16 v[82:97], v[174:177], v[230:233], v[66:81]
	s_waitcnt lgkmcnt(6)
	v_mfma_f32_32x32x16_bf16 v[66:81], v[190:193], v[230:233], v[66:81]
	ds_read_b128 v[126:129], v156
	ds_read_b128 v[122:125], v156 offset:4096
	s_waitcnt lgkmcnt(7)
	v_mfma_f32_32x32x16_bf16 v[82:97], v[178:181], v[234:237], v[82:97]
	s_waitcnt lgkmcnt(6)
	v_mfma_f32_32x32x16_bf16 v[66:81], v[194:197], v[234:237], v[66:81]
	ds_read_b128 v[118:121], v156 offset:8192
	ds_read_b128 v[114:117], v156 offset:12288
	s_waitcnt lgkmcnt(7)
	v_mfma_f32_32x32x16_bf16 v[82:97], v[182:185], v[242:245], v[82:97]
	s_waitcnt lgkmcnt(6)
	v_mfma_f32_32x32x16_bf16 v[66:81], v[198:201], v[242:245], v[66:81]
	ds_read_b128 v[110:113], v0
	ds_read_b128 v[106:109], v0 offset:4096
	s_waitcnt lgkmcnt(7)
	v_mfma_f32_32x32x16_bf16 v[82:97], v[186:189], v[246:249], v[82:97]
	s_waitcnt lgkmcnt(6)
	v_mfma_f32_32x32x16_bf16 v[66:81], v[220:223], v[246:249], v[66:81]
	ds_read_b128 v[102:105], v0 offset:8192
	ds_read_b128 v[98:101], v0 offset:12288
	s_cbranch_vccnz .LBB0_517
	v_add_u32_e32 v0, s26, v214
	v_add_u32_e32 v157, 0x18094, v0
	ds_read2_b32 v[158:159], v157 offset0:58 offset1:59
	ds_read2_b32 v[160:161], v157 offset0:26 offset1:27
	ds_read2_b32 v[162:163], v157 offset0:56 offset1:57
	ds_read2_b32 v[164:165], v157 offset0:24 offset1:25
	ds_read2_b32 v[166:167], v157 offset0:50 offset1:51
	ds_read2_b32 v[168:169], v157 offset0:18 offset1:19
	ds_read2_b32 v[174:175], v157 offset0:48 offset1:49
	ds_read2_b32 v[176:177], v157 offset0:16 offset1:17
	ds_read2_b32 v[178:179], v157 offset0:42 offset1:43
	ds_read2_b32 v[180:181], v157 offset0:10 offset1:11
	ds_read2_b32 v[182:183], v157 offset0:40 offset1:41
	ds_read2_b32 v[184:185], v157 offset0:8 offset1:9
	ds_read2_b32 v[190:191], v157 offset0:34 offset1:35
	ds_read2_b32 v[192:193], v157 offset0:2 offset1:3
	ds_read2_b32 v[194:195], v157 offset0:32 offset1:33
	ds_read2_b32 v[196:197], v157 offset0:0 offset1:1
	s_waitcnt lgkmcnt(0)
	v_pk_add_f32 v[82:83], v[82:83], v[158:159] op_sel:[0,1] op_sel_hi:[1,0]
	v_pk_add_f32 v[66:67], v[66:67], v[160:161] op_sel:[0,1] op_sel_hi:[1,0]
	v_pk_add_f32 v[84:85], v[84:85], v[162:163] op_sel:[0,1] op_sel_hi:[1,0]
	v_pk_add_f32 v[68:69], v[68:69], v[164:165] op_sel:[0,1] op_sel_hi:[1,0]
	v_pk_add_f32 v[86:87], v[86:87], v[166:167] op_sel:[0,1] op_sel_hi:[1,0]
	v_pk_add_f32 v[70:71], v[70:71], v[168:169] op_sel:[0,1] op_sel_hi:[1,0]
	v_pk_add_f32 v[88:89], v[88:89], v[174:175] op_sel:[0,1] op_sel_hi:[1,0]
	v_pk_add_f32 v[72:73], v[72:73], v[176:177] op_sel:[0,1] op_sel_hi:[1,0]
	v_pk_add_f32 v[90:91], v[90:91], v[178:179] op_sel:[0,1] op_sel_hi:[1,0]
	v_pk_add_f32 v[74:75], v[74:75], v[180:181] op_sel:[0,1] op_sel_hi:[1,0]
	v_pk_add_f32 v[92:93], v[92:93], v[182:183] op_sel:[0,1] op_sel_hi:[1,0]
	v_pk_add_f32 v[76:77], v[76:77], v[184:185] op_sel:[0,1] op_sel_hi:[1,0]
	v_pk_add_f32 v[94:95], v[94:95], v[190:191] op_sel:[0,1] op_sel_hi:[1,0]
	v_pk_add_f32 v[78:79], v[78:79], v[192:193] op_sel:[0,1] op_sel_hi:[1,0]
	v_pk_add_f32 v[96:97], v[96:97], v[194:195] op_sel:[0,1] op_sel_hi:[1,0]
	v_pk_add_f32 v[80:81], v[80:81], v[196:197] op_sel:[0,1] op_sel_hi:[1,0]
